# D1 too: residual base A1 pulled toward L2 during the K-loop (one wave per K-iteration 26+2w), on top of the W_out and D2 prefetches
# baseline (speedup 1.0000x reference)
; #define SEAM(k) do { if ((k) + 1 < ph_hi) xcd_barrier(xbar); } while (0)
; template <class Epi, class Sched, bool ALIGN_EPI = false, bool SP2 = false>
; __device__ __forceinline__ void gemm_phase(PG8_LAS unsigned char* lds, const Gemm g, const Sched& S, const Epi& E) {
;     const int tid = threadIdx.x, wid = __builtin_amdgcn_readfirstlane(tid >> 6), lane = tid & 63, wr = wid >> 2, wc = wid & 3, fr = lane & 15, fq = lane >> 4;
;     const int K = g.K, nt = K / BK;
;     unsigned voffA[2], voffB[2];
; #pragma unroll
;     for (int i = 0; i < 2; ++i) { int R, C; stage_rc(tid * 16 + i * 8192, R, C); const int Rb = Epi::PERM ? ((R & ~31) + perm32(R & 31)) : R;
;         voffA[i] = (unsigned)(R * K + C) * 2u; voffB[i] = (unsigned)(Rb * K + C) * 2u; }
;     const size_t kstep = (size_t)(BK * 2);
;     const size_t hstep = (size_t)HALF * K * 2;
;     const size_t tstep = 2 * hstep;
;     const unsigned ldsw = (unsigned)wid * 1024u;
;     const int aoff = lds_byte(wr * 64 + fr, fq * 8), boff = lds_byte(wc * 32 + fr, fq * 8);
;     ...
;     Unit cur, nxt; int ui = 0;
;     if (!S.next(0, cur)) return;
; __global__ void __launch_bounds__(NTHREADS, 2) mega(Params P, int ph_lo, int ph_hi) {
;     ...
;     if (IN(2)) { pg8::Gemm g{(const bf16*)(ws + OFF_ACT), (const bf16*)(ws + OFF_WD1), MMAIN, DM, DFF}; pg8::StaticOrder S; S.init(MMAIN, DM, G, (int)blockIdx.x);
;         pg8::EpiResid E{nullptr, (const bf16*)(ws + OFF_RA), (const float*)(ws + OFF_RMS0), nullptr, (bf16*)P.out, ss1, 0.5f};     pg8::gemm_phase<pg8::EpiResid, pg8::StaticOrder, true, true>(lds, g, S, E); meta_d1(P, lds, wid, G, lane); SEAM(2); }
.LBB0_290:
	s_cmp_gt_i32 s88, 2
	s_cselect_b64 s[0:1], -1, 0
	s_cmp_lt_i32 s89, 3
	s_cselect_b64 s[2:3], -1, 0
	s_or_b64 s[0:1], s[0:1], s[2:3]
	s_and_b64 vcc, exec, s[0:1]
	s_cbranch_vccnz .LBB0_400
	v_readfirstlane_b32 s101, v209
	v_lshrrev_b32_e32 v240, 1, v209
	v_and_b32_e32 v241, 1, v209
	v_lshlrev_b32_e32 v240, 11, v240
	v_lshl_add_u32 v240, v241, 8, v240
	s_lshr_b32 s101, s101, 6
	s_lshl_b32 s101, s101, 1
	s_add_i32 s101, s101, 26
	s_cmpk_lt_i32 s33, 0x100
	s_cselect_b64 s[0:1], -1, 0
	s_cmpk_gt_i32 s33, 0xff
	v_readfirstlane_b32 s4, v209
	s_cbranch_scc1 .LBB0_297
	s_ashr_i32 s2, s33, 31
	s_lshr_b32 s2, s2, 29
	s_add_i32 s5, s33, s2
	s_and_b32 s2, s5, -8
	s_sub_i32 s8, s33, s2
	s_cmp_gt_i32 s8, -1
	s_cbranch_scc0 .LBB0_294
	s_lshl_b32 s9, s8, 5
	s_cbranch_execz .LBB0_295
	s_branch .LBB0_296

; #define PG8_STAGE(bufoff, gbase, voff) do { _Pragma("unroll") for (int _i = 0; _i < 2; ++_i) \
;         __builtin_amdgcn_global_load_lds((const unsigned*)((const char*)(gbase) + (voff)[_i]), (PG8_LAS unsigned*)(lds + (bufoff) + ldsw + _i * 8192), 16, 0, 0); } while (0)
; #define PG8_LDA(dst, b, h) do { _Pragma("unroll") for (int m = 0; m < 4; ++m) _Pragma("unroll") for (int k = 0; k < 2; ++k) dst[m][k] = *(const PG8_LAS bf16x8*)(lds + PG8_SA(b, h) + aoff + m * 2048 + k * 1024); } while (0)
; #define PG8_LDB(dst, b, h) do { _Pragma("unroll") for (int n = 0; n < 2; ++n) _Pragma("unroll") for (int k = 0; k < 2; ++k) dst[n][k] = *(const PG8_LAS bf16x8*)(lds + PG8_SB(b, h) + boff + n * 2048 + k * 1024); } while (0)
; #define PG8_MMA(ai, bj, At, Bt) do { __builtin_amdgcn_s_setprio(1); _Pragma("unroll") for (int m = 0; m < 4; ++m) _Pragma("unroll") for (int n = 0; n < 2; ++n) _Pragma("unroll") for (int k = 0; k < 2; ++k) \
;         acc[ai][bj][m][n] = __builtin_amdgcn_mfma_f32_16x16x32_bf16(Bt[n][k], At[m][k], acc[ai][bj][m][n], 0, 0, 0); __builtin_amdgcn_s_setprio(0); } while (0)
; #define PG8_WAIT_V(n) asm volatile("s_waitcnt vmcnt(" #n ")" ::: "memory")
; #define PG8_WAIT_L(n) asm volatile("s_waitcnt lgkmcnt(" #n ")" ::: "memory")
; #define PG8_BAR __builtin_amdgcn_s_barrier()
; #define PG8_SCHED __builtin_amdgcn_sched_barrier(0)
; template <class Epi, class Sched, bool ALIGN_EPI = false, bool SP2 = false>
; __device__ __forceinline__ void gemm_phase(PG8_LAS unsigned char* lds, const Gemm g, const Sched& S, const Epi& E) {
;     ...
;             PG8_LDB(B0, 0, 0); PG8_LDB(B1, 0, 1); PG8_SCHED; PG8_LDA(At, 0, 0); PG8_STAGE(PG8_SA(1, 1), a1 + hstep, voffA);
;             PG8_WAIT_V(8); PG8_WAIT_L(0); PG8_BAR; PG8_MMA(0, 0, At, B0); PG8_MMA(0, 1, At, B1); PG8_BAR; PG8_SCHED;
;             PG8_LDA(At, 0, 1); PG8_STAGE(PG8_SB(0, 0), b2, voffB); PG8_STAGE(PG8_SB(0, 1), b2 + hstep, voffB); PG8_STAGE(PG8_SA(0, 0), a2, voffA);
;             PG8_WAIT_V(8); PG8_WAIT_L(0); PG8_BAR; PG8_MMA(1, 0, At, B0); PG8_MMA(1, 1, At, B1); PG8_BAR; PG8_SCHED;
.LBB0_314:
	ds_read_b128 v[144:147], v152
	ds_read_b128 v[156:159], v152 offset:1024
	ds_read_b128 v[160:163], v152 offset:2048
	ds_read_b128 v[164:167], v152 offset:3072
	ds_read_b128 v[168:171], v153
	ds_read_b128 v[172:175], v153 offset:1024
	ds_read_b128 v[176:179], v153 offset:2048
	ds_read_b128 v[180:183], v153 offset:3072
	s_add_u32 s26, s24, 0xfff50080
	s_addc_u32 s27, s25, -1
	s_cmp_eq_u32 s57, 40
	s_cselect_b32 s29, s1, s27
	s_cselect_b32 s28, s0, s26
	s_cselect_b32 s27, s23, s56
	s_cselect_b32 s26, s22, s53
	v_lshl_add_u64 v[218:219], s[24:25], 0, v[136:137]
	s_add_i32 m0, s37, 0xc000
	ds_read_b128 v[184:187], v154
	ds_read_b128 v[188:191], v154 offset:1024
	ds_read_b128 v[192:195], v154 offset:2048
	ds_read_b128 v[196:199], v154 offset:3072
	ds_read_b128 v[200:203], v154 offset:4096
	ds_read_b128 v[204:207], v154 offset:5120
	ds_read_b128 v[210:213], v154 offset:6144
	ds_read_b128 v[214:217], v154 offset:7168
	global_load_lds_dwordx4 v[218:219], off
	v_lshl_add_u64 v[218:219], s[24:25], 0, v[138:139]
	s_add_i32 m0, s37, 0xe000
	s_nop 0
	global_load_lds_dwordx4 v[218:219], off
	s_waitcnt vmcnt(8)
	s_waitcnt lgkmcnt(0)
	s_barrier
	s_cmp_eq_u32 s57, s101
	s_cbranch_scc0 .Lmy_pf2_skip
	s_lshl_b32 s98, s51, 19
	s_lshl_b32 s99, s52, 9
	s_add_i32 s98, s98, s99
	v_add_u32_e32 v241, s98, v240
	global_load_dword v242, v241, s[10:11]
	global_load_dword v242, v241, s[10:11] offset:128
.Lmy_pf2_skip:
	s_setprio 1
	s_waitcnt lgkmcnt(0)
	v_mfma_f32_16x16x32_bf16 v[124:127], v[144:147], v[184:187], v[124:127]
	v_mfma_f32_16x16x32_bf16 v[120:123], v[160:163], v[184:187], v[120:123]
	v_mfma_f32_16x16x32_bf16 v[108:111], v[144:147], v[192:195], v[108:111]
	v_mfma_f32_16x16x32_bf16 v[104:107], v[160:163], v[192:195], v[104:107]
	v_mfma_f32_16x16x32_bf16 v[92:95], v[144:147], v[200:203], v[92:95]
	v_mfma_f32_16x16x32_bf16 v[88:91], v[160:163], v[200:203], v[88:91]
	v_mfma_f32_16x16x32_bf16 v[76:79], v[144:147], v[210:213], v[76:79]
	v_mfma_f32_16x16x32_bf16 v[72:75], v[160:163], v[210:213], v[72:75]
	v_mfma_f32_16x16x32_bf16 v[124:127], v[156:159], v[188:191], v[124:127]
	v_mfma_f32_16x16x32_bf16 v[120:123], v[164:167], v[188:191], v[120:123]
	v_mfma_f32_16x16x32_bf16 v[108:111], v[156:159], v[196:199], v[108:111]
	v_mfma_f32_16x16x32_bf16 v[104:107], v[164:167], v[196:199], v[104:107]
	v_mfma_f32_16x16x32_bf16 v[92:95], v[156:159], v[204:207], v[92:95]
	v_mfma_f32_16x16x32_bf16 v[88:91], v[164:167], v[204:207], v[88:91]
	v_mfma_f32_16x16x32_bf16 v[76:79], v[156:159], v[214:217], v[76:79]
	v_mfma_f32_16x16x32_bf16 v[72:75], v[164:167], v[214:217], v[72:75]
	s_setprio 0
	s_setprio 1
	v_mfma_f32_16x16x32_bf16 v[116:119], v[168:171], v[184:187], v[116:119]
	v_mfma_f32_16x16x32_bf16 v[112:115], v[176:179], v[184:187], v[112:115]
	v_mfma_f32_16x16x32_bf16 v[100:103], v[168:171], v[192:195], v[100:103]
	v_mfma_f32_16x16x32_bf16 v[96:99], v[176:179], v[192:195], v[96:99]
	v_mfma_f32_16x16x32_bf16 v[84:87], v[168:171], v[200:203], v[84:87]
	v_mfma_f32_16x16x32_bf16 v[80:83], v[176:179], v[200:203], v[80:83]
	v_mfma_f32_16x16x32_bf16 v[68:71], v[168:171], v[210:213], v[68:71]
	v_mfma_f32_16x16x32_bf16 v[64:67], v[176:179], v[210:213], v[64:67]
	v_mfma_f32_16x16x32_bf16 v[116:119], v[172:175], v[188:191], v[116:119]
	v_mfma_f32_16x16x32_bf16 v[112:115], v[180:183], v[188:191], v[112:115]
	v_mfma_f32_16x16x32_bf16 v[100:103], v[172:175], v[196:199], v[100:103]
	v_mfma_f32_16x16x32_bf16 v[96:99], v[180:183], v[196:199], v[96:99]
	v_mfma_f32_16x16x32_bf16 v[84:87], v[172:175], v[204:207], v[84:87]
	v_mfma_f32_16x16x32_bf16 v[80:83], v[180:183], v[204:207], v[80:83]
	v_mfma_f32_16x16x32_bf16 v[68:71], v[172:175], v[214:217], v[68:71]
	v_mfma_f32_16x16x32_bf16 v[64:67], v[180:183], v[214:217], v[64:67]
	s_setprio 0
	s_barrier
	s_add_i32 s58, s47, s36
	v_lshl_add_u64 v[218:219], s[26:27], 0, v[130:131]
	s_mov_b32 m0, s58
	ds_read_b128 v[184:187], v154 offset:16384
	ds_read_b128 v[188:191], v154 offset:17408
	ds_read_b128 v[192:195], v154 offset:18432
	ds_read_b128 v[196:199], v154 offset:19456
	ds_read_b128 v[200:203], v154 offset:20480
	ds_read_b128 v[204:207], v154 offset:21504
	ds_read_b128 v[210:213], v154 offset:22528
	ds_read_b128 v[214:217], v154 offset:23552
	global_load_lds_dwordx4 v[218:219], off
	s_add_i32 m0, s58, 0x2000
	s_add_u32 s58, s26, 0xb0000
	v_lshl_add_u64 v[220:221], s[26:27], 0, v[134:135]
	s_addc_u32 s59, s27, 0
	s_add_i32 s60, s48, s36
	global_load_lds_dwordx4 v[220:221], off
	v_lshl_add_u64 v[222:223], s[58:59], 0, v[130:131]
	s_mov_b32 m0, s60
	v_lshl_add_u64 v[224:225], s[28:29], 0, v[132:133]
	global_load_lds_dwordx4 v[222:223], off
	v_lshl_add_u64 v[222:223], s[58:59], 0, v[134:135]
	s_add_i32 m0, s60, 0x2000
	s_nop 0
	global_load_lds_dwordx4 v[222:223], off
	v_lshl_add_u64 v[222:223], s[28:29], 0, v[128:129]
	s_mov_b32 m0, s37
	s_nop 0
	global_load_lds_dwordx4 v[222:223], off
	s_mov_b32 m0, s38
	s_nop 0
	global_load_lds_dwordx4 v[224:225], off
	s_waitcnt vmcnt(8)
	s_waitcnt lgkmcnt(0)
	s_barrier
; #define PG8_STAGE(bufoff, gbase, voff) do { _Pragma("unroll") for (int _i = 0; _i < 2; ++_i) \
;         __builtin_amdgcn_global_load_lds((const unsigned*)((const char*)(gbase) + (voff)[_i]), (PG8_LAS unsigned*)(lds + (bufoff) + ldsw + _i * 8192), 16, 0, 0); } while (0)
; #define PG8_LDA(dst, b, h) do { _Pragma("unroll") for (int m = 0; m < 4; ++m) _Pragma("unroll") for (int k = 0; k < 2; ++k) dst[m][k] = *(const PG8_LAS bf16x8*)(lds + PG8_SA(b, h) + aoff + m * 2048 + k * 1024); } while (0)
; #define PG8_LDB(dst, b, h) do { _Pragma("unroll") for (int n = 0; n < 2; ++n) _Pragma("unroll") for (int k = 0; k < 2; ++k) dst[n][k] = *(const PG8_LAS bf16x8*)(lds + PG8_SB(b, h) + boff + n * 2048 + k * 1024); } while (0)
; #define PG8_MMA(ai, bj, At, Bt) do { __builtin_amdgcn_s_setprio(1); _Pragma("unroll") for (int m = 0; m < 4; ++m) _Pragma("unroll") for (int n = 0; n < 2; ++n) _Pragma("unroll") for (int k = 0; k < 2; ++k) \
;         acc[ai][bj][m][n] = __builtin_amdgcn_mfma_f32_16x16x32_bf16(Bt[n][k], At[m][k], acc[ai][bj][m][n], 0, 0, 0); __builtin_amdgcn_s_setprio(0); } while (0)
; #define PG8_WAIT_V(n) asm volatile("s_waitcnt vmcnt(" #n ")" ::: "memory")
; #define PG8_WAIT_L(n) asm volatile("s_waitcnt lgkmcnt(" #n ")" ::: "memory")
; #define PG8_BAR __builtin_amdgcn_s_barrier()
; #define PG8_SCHED __builtin_amdgcn_sched_barrier(0)
; template <class Epi, class Sched, bool ALIGN_EPI = false, bool SP2 = false>
; __device__ __forceinline__ void gemm_phase(PG8_LAS unsigned char* lds, const Gemm g, const Sched& S, const Epi& E) {
;     ...
;             PG8_WAIT_V(8); PG8_WAIT_L(0); PG8_BAR; PG8_MMA(1, 0, At, B0); PG8_MMA(1, 1, At, B1); PG8_BAR; PG8_SCHED;
;             PG8_LDB(B0, 1, 0); PG8_LDB(B1, 1, 1); PG8_SCHED; PG8_LDA(At, 1, 0); PG8_STAGE(PG8_SA(0, 1), a2 + hstep, voffA);
;             PG8_WAIT_V(8); PG8_WAIT_L(0); PG8_BAR; PG8_MMA(0, 0, At, B0); PG8_MMA(0, 1, At, B1); PG8_BAR; PG8_SCHED;
	s_setprio 1
	s_waitcnt lgkmcnt(0)
	v_mfma_f32_16x16x32_bf16 v[60:63], v[144:147], v[184:187], v[60:63]
	v_mfma_f32_16x16x32_bf16 v[56:59], v[160:163], v[184:187], v[56:59]
	v_mfma_f32_16x16x32_bf16 v[44:47], v[144:147], v[192:195], v[44:47]
	v_mfma_f32_16x16x32_bf16 v[40:43], v[160:163], v[192:195], v[40:43]
	v_mfma_f32_16x16x32_bf16 v[28:31], v[144:147], v[200:203], v[28:31]
	v_mfma_f32_16x16x32_bf16 v[24:27], v[160:163], v[200:203], v[24:27]
	v_mfma_f32_16x16x32_bf16 v[12:15], v[144:147], v[210:213], v[12:15]
	v_mfma_f32_16x16x32_bf16 v[8:11], v[160:163], v[210:213], v[8:11]
	v_mfma_f32_16x16x32_bf16 v[60:63], v[156:159], v[188:191], v[60:63]
	v_mfma_f32_16x16x32_bf16 v[56:59], v[164:167], v[188:191], v[56:59]
	v_mfma_f32_16x16x32_bf16 v[44:47], v[156:159], v[196:199], v[44:47]
	v_mfma_f32_16x16x32_bf16 v[40:43], v[164:167], v[196:199], v[40:43]
	v_mfma_f32_16x16x32_bf16 v[28:31], v[156:159], v[204:207], v[28:31]
	v_mfma_f32_16x16x32_bf16 v[24:27], v[164:167], v[204:207], v[24:27]
	v_mfma_f32_16x16x32_bf16 v[12:15], v[156:159], v[214:217], v[12:15]
	v_mfma_f32_16x16x32_bf16 v[8:11], v[164:167], v[214:217], v[8:11]
	s_setprio 0
	s_setprio 1
	v_mfma_f32_16x16x32_bf16 v[52:55], v[168:171], v[184:187], v[52:55]
	v_mfma_f32_16x16x32_bf16 v[48:51], v[176:179], v[184:187], v[48:51]
	v_mfma_f32_16x16x32_bf16 v[36:39], v[168:171], v[192:195], v[36:39]
	v_mfma_f32_16x16x32_bf16 v[32:35], v[176:179], v[192:195], v[32:35]
	v_mfma_f32_16x16x32_bf16 v[20:23], v[168:171], v[200:203], v[20:23]
	v_mfma_f32_16x16x32_bf16 v[16:19], v[176:179], v[200:203], v[16:19]
	v_mfma_f32_16x16x32_bf16 v[4:7], v[168:171], v[210:213], v[4:7]
	v_mfma_f32_16x16x32_bf16 v[0:3], v[176:179], v[210:213], v[0:3]
	v_mfma_f32_16x16x32_bf16 v[52:55], v[172:175], v[188:191], v[52:55]
	v_mfma_f32_16x16x32_bf16 v[48:51], v[180:183], v[188:191], v[48:51]
	v_mfma_f32_16x16x32_bf16 v[36:39], v[172:175], v[196:199], v[36:39]
	v_mfma_f32_16x16x32_bf16 v[32:35], v[180:183], v[196:199], v[32:35]
	v_mfma_f32_16x16x32_bf16 v[20:23], v[172:175], v[204:207], v[20:23]
	v_mfma_f32_16x16x32_bf16 v[16:19], v[180:183], v[204:207], v[16:19]
	v_mfma_f32_16x16x32_bf16 v[4:7], v[172:175], v[214:217], v[4:7]
	v_mfma_f32_16x16x32_bf16 v[0:3], v[180:183], v[214:217], v[0:3]
	s_setprio 0
	s_barrier
	s_add_i32 s58, 0, 0x18000
	s_add_i32 s59, 0, 0x1c000
	v_add_u32_e32 v164, s58, v150
	v_add_u32_e32 v180, s59, v150
	ds_read_b128 v[144:147], v164
	ds_read_b128 v[156:159], v164 offset:1024
	ds_read_b128 v[160:163], v164 offset:2048
	ds_read_b128 v[164:167], v164 offset:3072
	ds_read_b128 v[168:171], v180
	ds_read_b128 v[172:175], v180 offset:1024
	ds_read_b128 v[176:179], v180 offset:2048
	ds_read_b128 v[180:183], v180 offset:3072
	s_add_u32 s28, s28, 0xb0000
	s_addc_u32 s29, s29, 0
	s_mov_b32 m0, s39
	v_lshl_add_u64 v[226:227], s[28:29], 0, v[128:129]
	ds_read_b128 v[184:187], v154 offset:32768
	ds_read_b128 v[188:191], v154 offset:33792
	ds_read_b128 v[192:195], v154 offset:34816
	ds_read_b128 v[196:199], v154 offset:35840
	ds_read_b128 v[200:203], v154 offset:36864
	ds_read_b128 v[204:207], v154 offset:37888
	ds_read_b128 v[210:213], v154 offset:38912
	ds_read_b128 v[214:217], v154 offset:39936
	global_load_lds_dwordx4 v[226:227], off
	v_lshl_add_u64 v[226:227], s[28:29], 0, v[132:133]
	s_mov_b32 m0, s40
	s_nop 0
	global_load_lds_dwordx4 v[226:227], off
	s_waitcnt vmcnt(8)
	s_waitcnt lgkmcnt(0)
	s_barrier
	s_setprio 1
	s_waitcnt lgkmcnt(0)
	v_mfma_f32_16x16x32_bf16 v[124:127], v[144:147], v[184:187], v[124:127]
	v_mfma_f32_16x16x32_bf16 v[120:123], v[160:163], v[184:187], v[120:123]
	v_mfma_f32_16x16x32_bf16 v[108:111], v[144:147], v[192:195], v[108:111]
	v_mfma_f32_16x16x32_bf16 v[104:107], v[160:163], v[192:195], v[104:107]
	v_mfma_f32_16x16x32_bf16 v[92:95], v[144:147], v[200:203], v[92:95]
	v_mfma_f32_16x16x32_bf16 v[88:91], v[160:163], v[200:203], v[88:91]
	v_mfma_f32_16x16x32_bf16 v[76:79], v[144:147], v[210:213], v[76:79]
	v_mfma_f32_16x16x32_bf16 v[72:75], v[160:163], v[210:213], v[72:75]
	v_mfma_f32_16x16x32_bf16 v[124:127], v[156:159], v[188:191], v[124:127]
	v_mfma_f32_16x16x32_bf16 v[120:123], v[164:167], v[188:191], v[120:123]
	v_mfma_f32_16x16x32_bf16 v[108:111], v[156:159], v[196:199], v[108:111]
	v_mfma_f32_16x16x32_bf16 v[104:107], v[164:167], v[196:199], v[104:107]
	v_mfma_f32_16x16x32_bf16 v[92:95], v[156:159], v[204:207], v[92:95]
	v_mfma_f32_16x16x32_bf16 v[88:91], v[164:167], v[204:207], v[88:91]
	v_mfma_f32_16x16x32_bf16 v[76:79], v[156:159], v[214:217], v[76:79]
	v_mfma_f32_16x16x32_bf16 v[72:75], v[164:167], v[214:217], v[72:75]
	s_setprio 0
	s_setprio 1
	v_mfma_f32_16x16x32_bf16 v[116:119], v[168:171], v[184:187], v[116:119]
	v_mfma_f32_16x16x32_bf16 v[112:115], v[176:179], v[184:187], v[112:115]
	v_mfma_f32_16x16x32_bf16 v[100:103], v[168:171], v[192:195], v[100:103]
	v_mfma_f32_16x16x32_bf16 v[96:99], v[176:179], v[192:195], v[96:99]
	v_mfma_f32_16x16x32_bf16 v[84:87], v[168:171], v[200:203], v[84:87]
	v_mfma_f32_16x16x32_bf16 v[80:83], v[176:179], v[200:203], v[80:83]
	v_mfma_f32_16x16x32_bf16 v[68:71], v[168:171], v[210:213], v[68:71]
	v_mfma_f32_16x16x32_bf16 v[64:67], v[176:179], v[210:213], v[64:67]
	v_mfma_f32_16x16x32_bf16 v[116:119], v[172:175], v[188:191], v[116:119]
	v_mfma_f32_16x16x32_bf16 v[112:115], v[180:183], v[188:191], v[112:115]
	v_mfma_f32_16x16x32_bf16 v[100:103], v[172:175], v[196:199], v[100:103]
	v_mfma_f32_16x16x32_bf16 v[96:99], v[180:183], v[196:199], v[96:99]
	v_mfma_f32_16x16x32_bf16 v[84:87], v[172:175], v[204:207], v[84:87]
	v_mfma_f32_16x16x32_bf16 v[80:83], v[180:183], v[204:207], v[80:83]
	v_mfma_f32_16x16x32_bf16 v[68:71], v[172:175], v[214:217], v[68:71]
	v_mfma_f32_16x16x32_bf16 v[64:67], v[180:183], v[214:217], v[64:67]
	s_setprio 0
	s_barrier
; #define PG8_STAGE(bufoff, gbase, voff) do { _Pragma("unroll") for (int _i = 0; _i < 2; ++_i) \
;         __builtin_amdgcn_global_load_lds((const unsigned*)((const char*)(gbase) + (voff)[_i]), (PG8_LAS unsigned*)(lds + (bufoff) + ldsw + _i * 8192), 16, 0, 0); } while (0)
; #define PG8_LDA(dst, b, h) do { _Pragma("unroll") for (int m = 0; m < 4; ++m) _Pragma("unroll") for (int k = 0; k < 2; ++k) dst[m][k] = *(const PG8_LAS bf16x8*)(lds + PG8_SA(b, h) + aoff + m * 2048 + k * 1024); } while (0)
; #define PG8_MMA(ai, bj, At, Bt) do { __builtin_amdgcn_s_setprio(1); _Pragma("unroll") for (int m = 0; m < 4; ++m) _Pragma("unroll") for (int n = 0; n < 2; ++n) _Pragma("unroll") for (int k = 0; k < 2; ++k) \
;         acc[ai][bj][m][n] = __builtin_amdgcn_mfma_f32_16x16x32_bf16(Bt[n][k], At[m][k], acc[ai][bj][m][n], 0, 0, 0); __builtin_amdgcn_s_setprio(0); } while (0)
; #define PG8_WAIT_V(n) asm volatile("s_waitcnt vmcnt(" #n ")" ::: "memory")
; #define PG8_WAIT_L(n) asm volatile("s_waitcnt lgkmcnt(" #n ")" ::: "memory")
; #define PG8_BAR __builtin_amdgcn_s_barrier()
; #define PG8_SCHED __builtin_amdgcn_sched_barrier(0)
; template <class Epi, class Sched, bool ALIGN_EPI = false, bool SP2 = false>
; __device__ __forceinline__ void gemm_phase(PG8_LAS unsigned char* lds, const Gemm g, const Sched& S, const Epi& E) {
;     ...
;             PG8_LDA(At, 1, 1); PG8_STAGE(PG8_SB(1, 0), b3, voffB); PG8_STAGE(PG8_SB(1, 1), b3 + hstep, voffB); PG8_STAGE(PG8_SA(1, 0), a3, voffA);
;             PG8_WAIT_V(8); PG8_WAIT_L(0); PG8_BAR; PG8_MMA(1, 0, At, B0); PG8_MMA(1, 1, At, B1); PG8_BAR; PG8_SCHED;
	s_add_i32 s28, s58, s36
	v_lshl_add_u64 v[218:219], v[218:219], 0, s[14:15]
	s_mov_b32 m0, s28
	ds_read_b128 v[184:187], v154 offset:49152
	ds_read_b128 v[188:191], v154 offset:50176
	ds_read_b128 v[192:195], v154 offset:51200
	ds_read_b128 v[196:199], v154 offset:52224
	ds_read_b128 v[200:203], v154 offset:53248
	ds_read_b128 v[204:207], v154 offset:54272
	ds_read_b128 v[210:213], v154 offset:55296
	ds_read_b128 v[214:217], v154 offset:56320
	global_load_lds_dwordx4 v[218:219], off
	s_add_i32 m0, s28, 0x2000
	s_add_u32 s26, s26, 0xb0080
	v_lshl_add_u64 v[218:219], v[220:221], 0, s[14:15]
	s_addc_u32 s27, s27, 0
	s_add_i32 s28, s59, s36
	global_load_lds_dwordx4 v[218:219], off
	v_lshl_add_u64 v[218:219], s[26:27], 0, v[130:131]
	s_mov_b32 m0, s28
	s_nop 0
	global_load_lds_dwordx4 v[218:219], off
	v_lshl_add_u64 v[218:219], s[26:27], 0, v[134:135]
	s_add_i32 m0, s28, 0x2000
	s_nop 0
	global_load_lds_dwordx4 v[218:219], off
	v_lshl_add_u64 v[218:219], v[222:223], 0, s[14:15]
	s_mov_b32 m0, s42
	s_nop 0
	global_load_lds_dwordx4 v[218:219], off
	v_lshl_add_u64 v[218:219], v[224:225], 0, s[14:15]
	s_mov_b32 m0, s43
	s_nop 0
	global_load_lds_dwordx4 v[218:219], off
	s_waitcnt vmcnt(8)
	s_waitcnt lgkmcnt(0)
	s_barrier
	s_setprio 1
	s_waitcnt lgkmcnt(0)
	v_mfma_f32_16x16x32_bf16 v[60:63], v[144:147], v[184:187], v[60:63]
	v_mfma_f32_16x16x32_bf16 v[56:59], v[160:163], v[184:187], v[56:59]
	v_mfma_f32_16x16x32_bf16 v[44:47], v[144:147], v[192:195], v[44:47]
	v_mfma_f32_16x16x32_bf16 v[40:43], v[160:163], v[192:195], v[40:43]
	v_mfma_f32_16x16x32_bf16 v[28:31], v[144:147], v[200:203], v[28:31]
	v_mfma_f32_16x16x32_bf16 v[24:27], v[160:163], v[200:203], v[24:27]
	v_mfma_f32_16x16x32_bf16 v[12:15], v[144:147], v[210:213], v[12:15]
	v_mfma_f32_16x16x32_bf16 v[8:11], v[160:163], v[210:213], v[8:11]
	v_mfma_f32_16x16x32_bf16 v[60:63], v[156:159], v[188:191], v[60:63]
	v_mfma_f32_16x16x32_bf16 v[56:59], v[164:167], v[188:191], v[56:59]
	v_mfma_f32_16x16x32_bf16 v[44:47], v[156:159], v[196:199], v[44:47]
	v_mfma_f32_16x16x32_bf16 v[40:43], v[164:167], v[196:199], v[40:43]
	v_mfma_f32_16x16x32_bf16 v[28:31], v[156:159], v[204:207], v[28:31]
	v_mfma_f32_16x16x32_bf16 v[24:27], v[164:167], v[204:207], v[24:27]
	v_mfma_f32_16x16x32_bf16 v[12:15], v[156:159], v[214:217], v[12:15]
	v_mfma_f32_16x16x32_bf16 v[8:11], v[164:167], v[214:217], v[8:11]
	s_setprio 0
	s_setprio 1
	v_mfma_f32_16x16x32_bf16 v[52:55], v[168:171], v[184:187], v[52:55]
	v_mfma_f32_16x16x32_bf16 v[48:51], v[176:179], v[184:187], v[48:51]
	v_mfma_f32_16x16x32_bf16 v[36:39], v[168:171], v[192:195], v[36:39]
	v_mfma_f32_16x16x32_bf16 v[32:35], v[176:179], v[192:195], v[32:35]
	v_mfma_f32_16x16x32_bf16 v[20:23], v[168:171], v[200:203], v[20:23]
	v_mfma_f32_16x16x32_bf16 v[16:19], v[176:179], v[200:203], v[16:19]
	v_mfma_f32_16x16x32_bf16 v[4:7], v[168:171], v[210:213], v[4:7]
	v_mfma_f32_16x16x32_bf16 v[0:3], v[176:179], v[210:213], v[0:3]
	v_mfma_f32_16x16x32_bf16 v[52:55], v[172:175], v[188:191], v[52:55]
	v_mfma_f32_16x16x32_bf16 v[48:51], v[180:183], v[188:191], v[48:51]
	v_mfma_f32_16x16x32_bf16 v[36:39], v[172:175], v[196:199], v[36:39]
	v_mfma_f32_16x16x32_bf16 v[32:35], v[180:183], v[196:199], v[32:35]
	v_mfma_f32_16x16x32_bf16 v[20:23], v[172:175], v[204:207], v[20:23]
	v_mfma_f32_16x16x32_bf16 v[16:19], v[180:183], v[204:207], v[16:19]
	v_mfma_f32_16x16x32_bf16 v[4:7], v[172:175], v[214:217], v[4:7]
	v_mfma_f32_16x16x32_bf16 v[0:3], v[180:183], v[214:217], v[0:3]
	s_setprio 0
	s_barrier
	s_add_i32 s57, s57, 2
	s_add_u32 s24, s24, 0x100
	s_addc_u32 s25, s25, 0
	s_add_u32 s53, s53, 0x100
	s_addc_u32 s56, s56, 0
	s_cmp_gt_u32 s57, 41
	s_cbranch_scc0 .LBB0_314
	s_and_b64 vcc, exec, s[16:17]
	s_cbranch_vccz .LBB0_317
	s_barrier
